# NA local tiles: each 16-query group reads one 32-key window starting at its own key offset (0/8/24/32) instead of 2-3 aligned 16-key subtiles: 4 score subtiles per tile instead of 5, 8+8 MFMAs instead
# baseline (speedup 1.0000x reference)
.LBB0_333:
	v_lshl_add_u32 v0, s34, 9, v115
	s_waitcnt lgkmcnt(0)
	v_mov_b32_e32 v12, v163
	v_ashrrev_i32_e32 v0, 9, v0
	v_bfe_u32 v5, v12, 7, 1
	s_movk_i32 s2, 0x1100
	v_or_b32_e32 v8, v5, v127
	v_mad_i32_i24 v139, v0, s2, v188
	v_lshrrev_b32_e32 v2, 1, v12
	v_and_b32_e32 v138, 15, v12
	v_bfe_u32 v7, v12, 4, 2
	v_mul_i32_i24_e32 v4, 0x1100, v0
	v_lshl_add_u32 v0, v8, 6, v139
	v_and_b32_e32 v6, 32, v2
	v_or3_b32 v122, v0, v6, v138
	v_lshlrev_b32_e32 v0, 4, v7
	v_lshl_add_u64 v[2:3], v[116:117], 0, v[0:1]
	s_movk_i32 s4, 0x1800
	v_or_b32_e32 v120, 16, v122
	v_bfe_u32 v141, v12, 3, 5
	v_mad_i64_i32 v[10:11], s[2:3], v122, s4, v[2:3]
	v_mad_i64_i32 v[2:3], s[2:3], v120, s4, v[2:3]
	v_add_u32_e32 v18, v139, v129
	v_or_b32_e32 v143, 32, v141
	v_and_b32_e32 v28, 0xff, v12
	global_load_dwordx4 v[38:41], v[10:11], off
	global_load_dwordx4 v[34:37], v[10:11], off offset:64
	global_load_dwordx4 v[46:49], v[2:3], off
	global_load_dwordx4 v[42:45], v[2:3], off offset:64
	v_readlane_b32 s6, v252, 60
	v_readlane_b32 s7, v252, 61
	v_add_lshl_u32 v50, v130, v28, 2
	v_mov_b32_e32 v51, 0
	v_cmp_ge_u32_e32 vcc, s12, v28
	v_lshl_add_u64 v[50:51], s[6:7], 0, v[50:51]
	global_load_dword v52, v[50:51], off
	s_and_saveexec_b64 s[6:7], vcc
	global_load_dword v53, v[50:51], off offset:1024
	s_mov_b64 exec, s[6:7]
	v_or_b32_e32 v0, v141, v18
	v_mov_b64_e32 v[2:3], s[26:27]
	v_lshlrev_b32_e32 v12, 3, v12
	v_or_b32_e32 v18, v143, v18
	v_mad_i64_i32 v[10:11], s[2:3], v0, s4, v[2:3]
	v_lshlrev_b32_e32 v0, 1, v114
	v_and_b32_e32 v124, 56, v12
	v_mad_i64_i32 v[2:3], s[2:3], v18, s4, v[2:3]
	v_lshl_add_u64 v[10:11], v[10:11], 0, v[0:1]
	v_lshlrev_b32_e32 v26, 1, v124
	v_mov_b32_e32 v27, v1
	v_lshl_add_u64 v[2:3], v[2:3], 0, v[0:1]
	v_lshl_add_u64 v[14:15], v[10:11], 0, v[26:27]
	s_movk_i32 s5, 0x1000
	v_lshl_add_u64 v[2:3], v[2:3], 0, v[26:27]
	global_load_dwordx4 v[10:13], v[14:15], off offset:2048
	global_load_dwordx4 v[18:21], v[2:3], off offset:2048
	v_add_co_u32_e32 v14, vcc, s5, v14
	v_readlane_b32 s2, v252, 60
	s_nop 0
	v_addc_co_u32_e32 v15, vcc, 0, v15, vcc
	global_load_dwordx4 v[14:17], v[14:15], off
	v_add_co_u32_e32 v2, vcc, s5, v2
	v_readlane_b32 s3, v252, 61
	s_nop 0
	v_addc_co_u32_e32 v3, vcc, 0, v3, vcc
	global_load_dwordx4 v[22:25], v[2:3], off
	v_mul_u32_u24_e32 v2, 0x48, v141
	v_lshlrev_b32_e32 v2, 1, v2
	v_add3_u32 v2, v222, v2, v26
	v_mov_b32_e32 v3, v1
	v_lshlrev_b32_e32 v9, 3, v7
	v_ashrrev_i32_e32 v123, 31, v122
	v_ashrrev_i32_e32 v121, 31, v120
	s_mov_b64 s[4:5], 0
	s_waitcnt vmcnt(3)
	ds_write_b128 v2, v[10:13]
	s_waitcnt vmcnt(1)
	ds_write_b128 v2, v[14:17] offset:18432
	ds_write_b128 v2, v[18:21] offset:4608
	s_waitcnt vmcnt(0)
	ds_write_b128 v2, v[22:25] offset:23040
	v_lshlrev_b32_e32 v10, 2, v28
	v_add_u32_e32 v11, v131, v10
	v_mul_f32_e32 v52, 0x3fb8aa3b, v52
	v_cmp_ge_u32_e32 vcc, s12, v28
	ds_write_b32 v11, v52
	s_and_saveexec_b64 s[4:5], vcc
	v_mul_f32_e32 v53, 0x3fb8aa3b, v53
	ds_write_b32 v11, v53 offset:1024
	s_or_b64 exec, exec, s[4:5]
	v_lshlrev_b32_e32 v134, 2, v7
	v_lshrrev_b32_e32 v7, 2, v138
	v_or_b32_e32 v3, v6, v138
	v_or_b32_e32 v135, v134, v7
	v_and_b32_e32 v7, 12, v10
	v_lshl_add_u32 v136, v7, 1, v222
	v_sub_u32_e64 v7, v3, 8 clamp
	v_sub_u32_e32 v7, v134, v7
	v_sub_u32_e64 v2, v8, 4 clamp
	v_add_u32_e32 v8, 1, v7
	v_cmp_gt_u32_e64 s[42:43], 16, v8
	v_add_u32_e32 v8, 2, v7
	v_cmp_gt_u32_e64 s[44:45], 16, v8
	v_add_u32_e32 v8, 3, v7
	v_cmp_gt_u32_e64 s[46:47], 16, v8
	v_add_u32_e32 v8, 17, v7
	v_cmp_gt_u32_e64 s[50:51], 16, v8
	v_add_u32_e32 v8, 18, v7
	v_cmp_gt_u32_e64 s[52:53], 16, v8
	v_add_u32_e32 v8, 19, v7
	v_cmp_gt_u32_e64 s[54:55], 16, v8
	v_and_b32_e32 v8, -16, v7
	s_movk_i32 s3, 0xffe0
	s_movk_i32 s6, 0xffd0
	v_cmp_eq_u32_e64 s[56:57], s3, v8
	v_cmp_eq_u32_e64 s[64:65], s6, v8
	v_add_u32_e32 v8, 49, v7
	v_min_u32_e32 v3, 40, v3
	v_cmp_gt_u32_e64 s[66:67], 16, v8
	v_add_u32_e32 v8, 50, v7
	v_sub_u32_e32 v3, v134, v3
	v_cmp_gt_u32_e64 s[68:69], 16, v8
	v_add_u32_e32 v8, -7, v3
	v_cmp_gt_u32_e64 s[74:75], 16, v8
	v_add_u32_e32 v8, -6, v3
	v_lshl_add_u32 v145, v9, 1, v222
	v_add_u32_e32 v9, 33, v7
	v_cmp_gt_u32_e64 s[76:77], 16, v8
	v_add_u32_e32 v8, -5, v3
	s_movk_i32 s2, 0xffef
	v_cmp_gt_u32_e64 s[58:59], 16, v9
	v_add_u32_e32 v9, 34, v7
	v_cmp_gt_u32_e64 s[78:79], 16, v8
	v_add_u32_e32 v8, 9, v3
	v_cmp_gt_u32_e64 s[40:41], 16, v7
	v_cmp_lt_u32_e64 s[48:49], s2, v7
	v_cmp_gt_u32_e64 s[60:61], 16, v9
	v_add_u32_e32 v9, 35, v7
	v_add_u32_e32 v7, 51, v7
	v_cmp_gt_u32_e64 s[82:83], 16, v8
	v_add_u32_e32 v8, 10, v3
	v_cmp_gt_u32_e64 s[70:71], 16, v7
	v_add_u32_e32 v7, -8, v3
	v_cmp_gt_u32_e64 s[84:85], 16, v8
	v_add_u32_e32 v8, 11, v3
	v_cmp_gt_u32_e64 s[72:73], 16, v7
	v_cmp_lt_u32_e64 s[80:81], s2, v7
	v_cmp_gt_u32_e64 s[86:87], 16, v8
	v_and_b32_e32 v7, -16, v7
	v_add_u32_e32 v8, 25, v3
	v_cmp_eq_u32_e64 s[88:89], s3, v7
	v_cmp_gt_u32_e64 s[90:91], 16, v8
	v_add_u32_e32 v8, 26, v3
	v_cmp_eq_u32_e64 s[94:95], s6, v7
	v_add_u32_e32 v7, 41, v3
	v_cmp_gt_u32_e64 s[92:93], 16, v8
	v_add_u32_e32 v8, 27, v3
	v_cmp_gt_u32_e64 s[6:7], 16, v7
	v_add_u32_e32 v7, 42, v3
	v_add_u32_e32 v3, 43, v3
	v_cmp_gt_u32_e64 s[96:97], 16, v3
	v_sub_u32_e32 v3, v132, v5
	v_sub_u32_e32 v5, v134, v138
	v_sub_u32_e32 v5, v5, v6
	v_min_u32_e32 v2, 56, v2
	v_mul_i32_i24_e32 v3, 0x7c, v3
	v_lshlrev_b32_e32 v5, 2, v5
	v_mov_b32_e32 v18, v1
	v_mov_b32_e32 v19, v1
	v_mov_b32_e32 v20, v1
	v_mov_b32_e32 v21, v1
	v_cmp_gt_u32_e64 s[62:63], 16, v9
	v_cmp_gt_u32_e64 s[4:5], 16, v8
	v_cmp_gt_u32_e64 s[8:9], 16, v7
	v_add3_u32 v147, v3, v5, v126
	v_sub_u32_e32 v148, v128, v2
	v_add_u32_e32 v149, 0xfffffe00, v4
	v_mov_b64_e32 v[32:33], v[20:21]
	v_mov_b64_e32 v[24:25], v[20:21]
	v_mov_b64_e32 v[28:29], v[20:21]
	v_mov_b64_e32 v[10:11], v[18:19]
	v_mov_b64_e32 v[14:15], v[18:19]
	v_mov_b64_e32 v[2:3], v[18:19]
	v_mov_b64_e32 v[6:7], v[18:19]
	v_lshl_add_u32 v146, v124, 1, v222
	s_mov_b32 s14, 0
	v_mov_b32_e32 v144, 0xf149f2ca
	v_mov_b32_e32 v140, 0
	v_mov_b64_e32 v[30:31], v[18:19]
	v_mov_b64_e32 v[22:23], v[18:19]
	v_mov_b64_e32 v[26:27], v[18:19]
	v_mov_b64_e32 v[12:13], v[20:21]
	v_mov_b64_e32 v[16:17], v[20:21]
	v_mov_b64_e32 v[4:5], v[20:21]
	v_mov_b64_e32 v[8:9], v[20:21]
	v_mov_b32_e32 v137, 0
	v_mov_b32_e32 v142, 0xf149f2ca
	s_mov_b32 s24, 0
	v_and_b32_e32 v66, 15, v163
	v_lshrrev_b32_e32 v67, 2, v163
	v_and_b32_e32 v67, 12, v67
	v_lshrrev_b32_e32 v68, 1, v163
	v_and_b32_e32 v68, 32, v68
	v_add_u32_e32 v66, v68, v66
	v_lshrrev_b32_e32 v69, 2, v68
	v_sub_u32_e32 v68, v68, v69
	v_sub_u32_e64 v69, v66, 8 clamp
	v_min_u32_e32 v69, 48, v69
	v_add_u32_e32 v70, 8, v66
	v_min_u32_e32 v70, 48, v70
	v_sub_u32_e32 v69, v67, v69
	v_add_u32_e32 v69, v69, v68
	v_sub_u32_e32 v70, v67, v70
	v_add3_u32 v70, v70, v68, 8
	v_add_u32_e32 v71, 0, v69
	v_cmp_gt_u32_e64 s[40:41], 16, v71
	v_add_u32_e32 v71, 1, v69
	v_cmp_gt_u32_e64 s[42:43], 16, v71
	v_add_u32_e32 v71, 2, v69
	v_cmp_gt_u32_e64 s[44:45], 16, v71
	v_add_u32_e32 v71, 3, v69
	v_cmp_gt_u32_e64 s[46:47], 16, v71
	v_add_u32_e32 v71, 16, v69
	v_cmp_gt_u32_e64 s[48:49], 16, v71
	v_add_u32_e32 v71, 17, v69
	v_cmp_gt_u32_e64 s[50:51], 16, v71
	v_add_u32_e32 v71, 18, v69
	v_cmp_gt_u32_e64 s[52:53], 16, v71
	v_add_u32_e32 v71, 19, v69
	v_cmp_gt_u32_e64 s[54:55], 16, v71
	v_add_u32_e32 v71, 0, v70
	v_cmp_gt_u32_e64 s[72:73], 16, v71
	v_add_u32_e32 v71, 1, v70
	v_cmp_gt_u32_e64 s[74:75], 16, v71
	v_add_u32_e32 v71, 2, v70
	v_cmp_gt_u32_e64 s[76:77], 16, v71
	v_add_u32_e32 v71, 3, v70
	v_cmp_gt_u32_e64 s[78:79], 16, v71
	v_add_u32_e32 v71, 16, v70
	v_cmp_gt_u32_e64 s[80:81], 16, v71
	v_add_u32_e32 v71, 17, v70
	v_cmp_gt_u32_e64 s[82:83], 16, v71
	v_add_u32_e32 v71, 18, v70
	v_cmp_gt_u32_e64 s[84:85], 16, v71
	v_add_u32_e32 v71, 19, v70
	v_cmp_gt_u32_e64 s[86:87], 16, v71
	s_waitcnt lgkmcnt(0)
	s_barrier
	s_branch .LBB0_338

.LBB0_342:
	v_add_u32_e32 v50, v58, v141
	v_mov_b64_e32 v[60:61], s[26:27]
	s_movk_i32 s10, 0x1800
	v_mad_i64_i32 v[50:51], s[2:3], v50, s10, v[60:61]
	v_lshl_add_u64 v[50:51], v[50:51], 0, v[0:1]
	v_lshlrev_b32_e32 v62, 1, v124
	v_mov_b32_e32 v63, v1
	v_add_u32_e32 v58, v58, v143
	v_lshl_add_u64 v[50:51], v[50:51], 0, v[62:63]
	v_mad_i64_i32 v[58:59], s[2:3], v58, s10, v[60:61]
	v_add_co_u32_e32 v54, vcc, 0x1000, v50
	v_lshl_add_u64 v[58:59], v[58:59], 0, v[0:1]
	s_nop 0
	v_addc_co_u32_e32 v55, vcc, 0, v51, vcc
	v_lshl_add_u64 v[58:59], v[58:59], 0, v[62:63]
	v_add_co_u32_e32 v62, vcc, 0x1000, v58
	global_load_dwordx4 v[50:53], v[50:51], off offset:2048
	s_nop 0
	global_load_dwordx4 v[54:57], v[54:55], off
	v_addc_co_u32_e32 v63, vcc, 0, v59, vcc
	global_load_dwordx4 v[58:61], v[58:59], off offset:2048
	s_nop 0
	global_load_dwordx4 v[62:65], v[62:63], off
	s_and_b32 s15, s14, 64
	v_add_u32_e32 v66, s24, v148
	s_cmp_gt_u32 s24, 8
	s_cselect_b64 s[10:11], -1, 0
	s_cmp_lt_u32 s24, 9
	v_cmp_gt_u32_e32 vcc, 8, v66
	s_movk_i32 s13, 0x1800
	s_cselect_b64 s[28:29], -1, 0
	s_or_b64 s[2:3], s[10:11], vcc
	s_and_saveexec_b64 s[38:39], s[2:3]
	s_cbranch_execz .LBB0_337
	v_or_b32_e32 v66, s15, v138
	v_mad_u32_u24 v82, v66, s16, v145
	s_cmp_lt_u32 s24, 9
	s_cbranch_scc0 .Lna_ctx_tile
	s_bitcmp1_b32 s100, 6
	s_cbranch_scc1 .Lna_loc_h1
	ds_read_b128 v[164:167], v82 offset:0
	ds_read_b128 v[168:171], v82 offset:64
	ds_read_b128 v[172:175], v82 offset:2304
	ds_read_b128 v[176:179], v82 offset:2368
	ds_read2_b32 v[224:225], v147 offset0:16 offset1:17
	ds_read2_b32 v[226:227], v147 offset0:18 offset1:19
	ds_read2_b32 v[228:229], v147 offset0:32 offset1:33
	ds_read2_b32 v[230:231], v147 offset0:34 offset1:35
	ds_read_b128 v[180:183], v82 offset:1152
	ds_read_b128 v[184:187], v82 offset:1216
	ds_read_b128 v[154:157], v82 offset:3456
	ds_read_b128 v[200:203], v82 offset:3520
	v_mov_b32_e32 v158, 0xf149f2ca
	s_waitcnt lgkmcnt(11)
	v_mfma_f32_16x16x32_bf16 v[90:93], v[164:167], v[38:41], 0
	s_waitcnt lgkmcnt(9)
	v_mfma_f32_16x16x32_bf16 v[94:97], v[172:175], v[38:41], 0
	v_mfma_f32_16x16x32_bf16 v[90:93], v[168:171], v[34:37], v[90:93]
	s_waitcnt lgkmcnt(8)
	v_mfma_f32_16x16x32_bf16 v[94:97], v[176:179], v[34:37], v[94:97]
	ds_read2_b32 v[232:233], v147 offset0:8 offset1:9
	ds_read2_b32 v[234:235], v147 offset0:10 offset1:11
	ds_read2_b32 v[236:237], v147 offset0:24 offset1:25
	ds_read2_b32 v[238:239], v147 offset0:26 offset1:27
	s_waitcnt lgkmcnt(7)
	v_mfma_f32_16x16x32_bf16 v[98:101], v[180:183], v[46:49], 0
	v_or_b32_e32 v160, s15, v135
	v_mul_u32_u24_e32 v160, 0x48, v160
	v_lshl_add_u32 v160, v160, 1, v136
	v_fmac_f32_e32 v224, 0x3e38aa3b, v90
	v_fmac_f32_e32 v225, 0x3e38aa3b, v91
	v_fmac_f32_e32 v226, 0x3e38aa3b, v92
	s_waitcnt lgkmcnt(5)
	v_mfma_f32_16x16x32_bf16 v[102:105], v[154:157], v[46:49], 0
	v_fmac_f32_e32 v227, 0x3e38aa3b, v93
	v_fmac_f32_e32 v228, 0x3e38aa3b, v94
	v_fmac_f32_e32 v229, 0x3e38aa3b, v95
	v_fmac_f32_e32 v230, 0x3e38aa3b, v96
	v_fmac_f32_e32 v231, 0x3e38aa3b, v97
	v_cndmask_b32_e64 v224, v158, v224, s[40:41]
	v_mfma_f32_16x16x32_bf16 v[98:101], v[184:187], v[42:45], v[98:101]
	v_cndmask_b32_e64 v225, v158, v225, s[42:43]
	v_cndmask_b32_e64 v226, v158, v226, s[44:45]
	v_cndmask_b32_e64 v227, v158, v227, s[46:47]
	v_cndmask_b32_e64 v228, v158, v228, s[48:49]
	v_cndmask_b32_e64 v229, v158, v229, s[50:51]
	v_cndmask_b32_e64 v230, v158, v230, s[52:53]
	s_waitcnt lgkmcnt(4)
	v_mfma_f32_16x16x32_bf16 v[102:105], v[200:203], v[42:45], v[102:105]
	v_cndmask_b32_e64 v231, v158, v231, s[54:55]
	v_max3_f32 v150, v224, s18, v225
	v_max3_f32 v150, v150, v226, v227
	v_max3_f32 v150, v150, v228, v229
	v_max3_f32 v150, v150, v230, v231
	s_waitcnt lgkmcnt(0)
	ds_read_b64_tr_b16 v[164:165], v160 offset:18432
	ds_read_b64_tr_b16 v[166:167], v160 offset:20736
	ds_read_b64_tr_b16 v[168:169], v160 offset:18464
	ds_read_b64_tr_b16 v[170:171], v160 offset:20768
	ds_read_b64_tr_b16 v[172:173], v160 offset:18496
	ds_read_b64_tr_b16 v[174:175], v160 offset:20800
	ds_read_b64_tr_b16 v[176:177], v160 offset:18528
	ds_read_b64_tr_b16 v[178:179], v160 offset:20832
	v_fmac_f32_e32 v232, 0x3e38aa3b, v98
	v_fmac_f32_e32 v233, 0x3e38aa3b, v99
	v_fmac_f32_e32 v234, 0x3e38aa3b, v100
	v_fmac_f32_e32 v235, 0x3e38aa3b, v101
	v_fmac_f32_e32 v236, 0x3e38aa3b, v102
	v_fmac_f32_e32 v237, 0x3e38aa3b, v103
	v_fmac_f32_e32 v238, 0x3e38aa3b, v104
	v_fmac_f32_e32 v239, 0x3e38aa3b, v105
	v_cndmask_b32_e64 v232, v158, v232, s[72:73]
	v_cndmask_b32_e64 v233, v158, v233, s[74:75]
	v_cndmask_b32_e64 v234, v158, v234, s[76:77]
	v_cndmask_b32_e64 v235, v158, v235, s[78:79]
	v_cndmask_b32_e64 v236, v158, v236, s[80:81]
	v_cndmask_b32_e64 v237, v158, v237, s[82:83]
	v_cndmask_b32_e64 v238, v158, v238, s[84:85]
	v_cndmask_b32_e64 v239, v158, v239, s[86:87]
	v_max3_f32 v151, v232, s18, v233
	v_max3_f32 v151, v151, v234, v235
	v_max3_f32 v151, v151, v236, v237
	v_max3_f32 v151, v151, v238, v239
	v_mov_b32_e32 v152, v150
	v_mov_b32_e32 v153, v151
	s_nop 0
	v_permlane16_swap_b32_e32 v152, v150
	v_permlane16_swap_b32_e32 v153, v151
	v_max_f32_e32 v150, v150, v152
	v_max_f32_e32 v151, v151, v153
	v_mov_b32_e32 v152, v150
	v_mov_b32_e32 v153, v151
	s_nop 0
	v_permlane32_swap_b32_e32 v152, v150
	v_permlane32_swap_b32_e32 v153, v151
	v_max_f32_e32 v150, v150, v152
	v_max_f32_e32 v151, v151, v153
	v_add_f32_e32 v110, 0x41000000, v144
	v_cmp_gt_f32_e32 vcc, v150, v110
	s_cbranch_vccz .Lna_l0_keep0
	v_max_f32_e32 v244, v144, v150
	v_sub_f32_e32 v110, v144, v244
	v_exp_f32_e32 v110, v110
	v_mov_b32_e32 v144, v244
	v_mul_f32_e32 v140, v140, v110
	v_pk_mul_f32 v[18:19], v[18:19], v[110:111] op_sel_hi:[1,0]
	v_pk_mul_f32 v[20:21], v[20:21], v[110:111] op_sel_hi:[1,0]
	v_pk_mul_f32 v[22:23], v[22:23], v[110:111] op_sel_hi:[1,0]
	v_pk_mul_f32 v[24:25], v[24:25], v[110:111] op_sel_hi:[1,0]
	v_pk_mul_f32 v[10:11], v[10:11], v[110:111] op_sel_hi:[1,0]
	v_pk_mul_f32 v[12:13], v[12:13], v[110:111] op_sel_hi:[1,0]
	v_pk_mul_f32 v[2:3], v[2:3], v[110:111] op_sel_hi:[1,0]
	v_pk_mul_f32 v[4:5], v[4:5], v[110:111] op_sel_hi:[1,0]

.Lna_l0_keep1:
	s_waitcnt lgkmcnt(6)
	ds_read_b64_tr_b16 v[180:181], v160 offset:19584
	ds_read_b64_tr_b16 v[182:183], v160 offset:21888
	ds_read_b64_tr_b16 v[184:185], v160 offset:19616
	ds_read_b64_tr_b16 v[186:187], v160 offset:21920
	ds_read_b64_tr_b16 v[154:155], v160 offset:19648
	ds_read_b64_tr_b16 v[156:157], v160 offset:21952
	ds_read_b64_tr_b16 v[200:201], v160 offset:19680
	ds_read_b64_tr_b16 v[202:203], v160 offset:21984
	v_sub_f32_e32 v224, v224, v144
	v_sub_f32_e32 v225, v225, v144
	v_exp_f32_e32 v224, v224
	v_sub_f32_e32 v226, v226, v144
	v_exp_f32_e32 v225, v225
	v_sub_f32_e32 v227, v227, v144
	v_exp_f32_e32 v226, v226
	v_exp_f32_e32 v227, v227
	v_sub_f32_e32 v228, v228, v144
	v_sub_f32_e32 v229, v229, v144
	v_exp_f32_e32 v228, v228
	v_sub_f32_e32 v230, v230, v144
	v_exp_f32_e32 v229, v229
	v_sub_f32_e32 v231, v231, v144
	v_exp_f32_e32 v230, v230
	v_exp_f32_e32 v231, v231
	v_add_f32_e32 v246, 0, v224
	v_add_f32_e32 v246, v225, v246
	v_add_f32_e32 v246, v226, v246
	v_add_f32_e32 v246, v227, v246
	v_cvt_pk_bf16_f32 v66, v224, v225
	v_cvt_pk_bf16_f32 v67, v226, v227
	v_add_f32_e32 v246, v228, v246
	v_add_f32_e32 v246, v229, v246
	v_add_f32_e32 v246, v230, v246
	v_add_f32_e32 v246, v231, v246
	v_cvt_pk_bf16_f32 v68, v228, v229
	v_cvt_pk_bf16_f32 v69, v230, v231
	v_add_f32_e32 v140, v140, v246
	s_nop 0
	v_mfma_f32_16x16x32_bf16 v[18:21], v[164:167], v[66:69], v[18:21]
	v_sub_f32_e32 v232, v232, v142
	v_sub_f32_e32 v233, v233, v142
	v_exp_f32_e32 v232, v232
	v_sub_f32_e32 v234, v234, v142
	v_exp_f32_e32 v233, v233
	v_sub_f32_e32 v235, v235, v142
	v_exp_f32_e32 v234, v234
	v_exp_f32_e32 v235, v235
	s_waitcnt lgkmcnt(12)
	v_mfma_f32_16x16x32_bf16 v[22:25], v[168:171], v[66:69], v[22:25]
	v_sub_f32_e32 v236, v236, v142
	v_sub_f32_e32 v237, v237, v142
	v_exp_f32_e32 v236, v236
	v_sub_f32_e32 v238, v238, v142
	v_exp_f32_e32 v237, v237
	v_sub_f32_e32 v239, v239, v142
	v_exp_f32_e32 v238, v238
	v_exp_f32_e32 v239, v239
	s_waitcnt lgkmcnt(10)
	v_mfma_f32_16x16x32_bf16 v[10:13], v[172:175], v[66:69], v[10:13]
	v_add_f32_e32 v247, 0, v232
	v_add_f32_e32 v247, v233, v247
	v_add_f32_e32 v247, v234, v247
	v_add_f32_e32 v247, v235, v247
	v_cvt_pk_bf16_f32 v74, v232, v233
	v_cvt_pk_bf16_f32 v75, v234, v235
	v_add_f32_e32 v247, v236, v247
	v_add_f32_e32 v247, v237, v247
	s_waitcnt lgkmcnt(8)
	v_mfma_f32_16x16x32_bf16 v[2:5], v[176:179], v[66:69], v[2:5]
	v_add_f32_e32 v247, v238, v247
	v_add_f32_e32 v247, v239, v247
	v_cvt_pk_bf16_f32 v76, v236, v237
	v_cvt_pk_bf16_f32 v77, v238, v239
	v_add_f32_e32 v137, v137, v247
	s_waitcnt lgkmcnt(6)
	v_mfma_f32_16x16x32_bf16 v[30:33], v[180:183], v[74:77], v[30:33]
	s_waitcnt lgkmcnt(4)
	v_mfma_f32_16x16x32_bf16 v[26:29], v[184:187], v[74:77], v[26:29]
	s_waitcnt lgkmcnt(2)
	v_mfma_f32_16x16x32_bf16 v[14:17], v[154:157], v[74:77], v[14:17]
	s_waitcnt lgkmcnt(0)
	v_mfma_f32_16x16x32_bf16 v[6:9], v[200:203], v[74:77], v[6:9]
	s_branch .LBB0_337
.Lna_loc_h1:
	ds_read_b128 v[164:167], v82 offset:3456
	ds_read_b128 v[168:171], v82 offset:3520
	ds_read_b128 v[172:175], v82 offset:5760
	ds_read_b128 v[176:179], v82 offset:5824
	ds_read2_b32 v[224:225], v147 offset0:40 offset1:41
	ds_read2_b32 v[226:227], v147 offset0:42 offset1:43
	ds_read2_b32 v[228:229], v147 offset0:56 offset1:57
	ds_read2_b32 v[230:231], v147 offset0:58 offset1:59
	ds_read_b128 v[180:183], v82 offset:4608
	ds_read_b128 v[184:187], v82 offset:4672
	ds_read_b128 v[154:157], v82 offset:6912
	ds_read_b128 v[200:203], v82 offset:6976
	v_mov_b32_e32 v158, 0xf149f2ca
	s_waitcnt lgkmcnt(11)
	v_mfma_f32_16x16x32_bf16 v[90:93], v[164:167], v[38:41], 0
	s_waitcnt lgkmcnt(9)
	v_mfma_f32_16x16x32_bf16 v[94:97], v[172:175], v[38:41], 0
	v_mfma_f32_16x16x32_bf16 v[90:93], v[168:171], v[34:37], v[90:93]
	s_waitcnt lgkmcnt(8)
	v_mfma_f32_16x16x32_bf16 v[94:97], v[176:179], v[34:37], v[94:97]
	ds_read2_b32 v[232:233], v147 offset0:32 offset1:33
	ds_read2_b32 v[234:235], v147 offset0:34 offset1:35
	ds_read2_b32 v[236:237], v147 offset0:48 offset1:49
	ds_read2_b32 v[238:239], v147 offset0:50 offset1:51
	s_waitcnt lgkmcnt(7)
	v_mfma_f32_16x16x32_bf16 v[98:101], v[180:183], v[46:49], 0
	v_or_b32_e32 v160, s15, v135
	v_mul_u32_u24_e32 v160, 0x48, v160
	v_lshl_add_u32 v160, v160, 1, v136
	v_fmac_f32_e32 v224, 0x3e38aa3b, v90
	v_fmac_f32_e32 v225, 0x3e38aa3b, v91
	v_fmac_f32_e32 v226, 0x3e38aa3b, v92
	s_waitcnt lgkmcnt(5)
	v_mfma_f32_16x16x32_bf16 v[102:105], v[154:157], v[46:49], 0
	v_fmac_f32_e32 v227, 0x3e38aa3b, v93
	v_fmac_f32_e32 v228, 0x3e38aa3b, v94
	v_fmac_f32_e32 v229, 0x3e38aa3b, v95
	v_fmac_f32_e32 v230, 0x3e38aa3b, v96
	v_fmac_f32_e32 v231, 0x3e38aa3b, v97
	v_cndmask_b32_e64 v224, v158, v224, s[40:41]
	v_mfma_f32_16x16x32_bf16 v[98:101], v[184:187], v[42:45], v[98:101]
	v_cndmask_b32_e64 v225, v158, v225, s[42:43]
	v_cndmask_b32_e64 v226, v158, v226, s[44:45]
	v_cndmask_b32_e64 v227, v158, v227, s[46:47]
	v_cndmask_b32_e64 v228, v158, v228, s[48:49]
	v_cndmask_b32_e64 v229, v158, v229, s[50:51]
	v_cndmask_b32_e64 v230, v158, v230, s[52:53]
	s_waitcnt lgkmcnt(4)
	v_mfma_f32_16x16x32_bf16 v[102:105], v[200:203], v[42:45], v[102:105]
	v_cndmask_b32_e64 v231, v158, v231, s[54:55]
	v_max3_f32 v150, v224, s18, v225
	v_max3_f32 v150, v150, v226, v227
	v_max3_f32 v150, v150, v228, v229
	v_max3_f32 v150, v150, v230, v231
	s_waitcnt lgkmcnt(0)
	ds_read_b64_tr_b16 v[164:165], v160 offset:21888
	ds_read_b64_tr_b16 v[166:167], v160 offset:24192
	ds_read_b64_tr_b16 v[168:169], v160 offset:21920
	ds_read_b64_tr_b16 v[170:171], v160 offset:24224
	ds_read_b64_tr_b16 v[172:173], v160 offset:21952
	ds_read_b64_tr_b16 v[174:175], v160 offset:24256
	ds_read_b64_tr_b16 v[176:177], v160 offset:21984
	ds_read_b64_tr_b16 v[178:179], v160 offset:24288
	v_fmac_f32_e32 v232, 0x3e38aa3b, v98
	v_fmac_f32_e32 v233, 0x3e38aa3b, v99
	v_fmac_f32_e32 v234, 0x3e38aa3b, v100
	v_fmac_f32_e32 v235, 0x3e38aa3b, v101
	v_fmac_f32_e32 v236, 0x3e38aa3b, v102
	v_fmac_f32_e32 v237, 0x3e38aa3b, v103
	v_fmac_f32_e32 v238, 0x3e38aa3b, v104
	v_fmac_f32_e32 v239, 0x3e38aa3b, v105
	v_cndmask_b32_e64 v232, v158, v232, s[72:73]
	v_cndmask_b32_e64 v233, v158, v233, s[74:75]
	v_cndmask_b32_e64 v234, v158, v234, s[76:77]
	v_cndmask_b32_e64 v235, v158, v235, s[78:79]
	v_cndmask_b32_e64 v236, v158, v236, s[80:81]
	v_cndmask_b32_e64 v237, v158, v237, s[82:83]
	v_cndmask_b32_e64 v238, v158, v238, s[84:85]
	v_cndmask_b32_e64 v239, v158, v239, s[86:87]
	v_max3_f32 v151, v232, s18, v233
	v_max3_f32 v151, v151, v234, v235
	v_max3_f32 v151, v151, v236, v237
	v_max3_f32 v151, v151, v238, v239
	v_mov_b32_e32 v152, v150
	v_mov_b32_e32 v153, v151
	s_nop 0
	v_permlane16_swap_b32_e32 v152, v150
	v_permlane16_swap_b32_e32 v153, v151
	v_max_f32_e32 v150, v150, v152
	v_max_f32_e32 v151, v151, v153
	v_mov_b32_e32 v152, v150
	v_mov_b32_e32 v153, v151
	s_nop 0
	v_permlane32_swap_b32_e32 v152, v150
	v_permlane32_swap_b32_e32 v153, v151
	v_max_f32_e32 v150, v150, v152
	v_max_f32_e32 v151, v151, v153
	v_add_f32_e32 v110, 0x41000000, v144
	v_cmp_gt_f32_e32 vcc, v150, v110
	s_cbranch_vccz .Lna_l1_keep0
	v_max_f32_e32 v244, v144, v150
	v_sub_f32_e32 v110, v144, v244
	v_exp_f32_e32 v110, v110
	v_mov_b32_e32 v144, v244
	v_mul_f32_e32 v140, v140, v110
	v_pk_mul_f32 v[18:19], v[18:19], v[110:111] op_sel_hi:[1,0]
	v_pk_mul_f32 v[20:21], v[20:21], v[110:111] op_sel_hi:[1,0]
	v_pk_mul_f32 v[22:23], v[22:23], v[110:111] op_sel_hi:[1,0]
	v_pk_mul_f32 v[24:25], v[24:25], v[110:111] op_sel_hi:[1,0]
	v_pk_mul_f32 v[10:11], v[10:11], v[110:111] op_sel_hi:[1,0]
	v_pk_mul_f32 v[12:13], v[12:13], v[110:111] op_sel_hi:[1,0]
	v_pk_mul_f32 v[2:3], v[2:3], v[110:111] op_sel_hi:[1,0]
	v_pk_mul_f32 v[4:5], v[4:5], v[110:111] op_sel_hi:[1,0]

.Lna_l1_keep1:
	s_waitcnt lgkmcnt(6)
	ds_read_b64_tr_b16 v[180:181], v160 offset:23040
	ds_read_b64_tr_b16 v[182:183], v160 offset:25344
	ds_read_b64_tr_b16 v[184:185], v160 offset:23072
	ds_read_b64_tr_b16 v[186:187], v160 offset:25376
	ds_read_b64_tr_b16 v[154:155], v160 offset:23104
	ds_read_b64_tr_b16 v[156:157], v160 offset:25408
	ds_read_b64_tr_b16 v[200:201], v160 offset:23136
	ds_read_b64_tr_b16 v[202:203], v160 offset:25440
	v_sub_f32_e32 v224, v224, v144
	v_sub_f32_e32 v225, v225, v144
	v_exp_f32_e32 v224, v224
	v_sub_f32_e32 v226, v226, v144
	v_exp_f32_e32 v225, v225
	v_sub_f32_e32 v227, v227, v144
	v_exp_f32_e32 v226, v226
	v_exp_f32_e32 v227, v227
	v_sub_f32_e32 v228, v228, v144
	v_sub_f32_e32 v229, v229, v144
	v_exp_f32_e32 v228, v228
	v_sub_f32_e32 v230, v230, v144
	v_exp_f32_e32 v229, v229
	v_sub_f32_e32 v231, v231, v144
	v_exp_f32_e32 v230, v230
	v_exp_f32_e32 v231, v231
	v_add_f32_e32 v246, 0, v224
	v_add_f32_e32 v246, v225, v246
	v_add_f32_e32 v246, v226, v246
	v_add_f32_e32 v246, v227, v246
	v_cvt_pk_bf16_f32 v66, v224, v225
	v_cvt_pk_bf16_f32 v67, v226, v227
	v_add_f32_e32 v246, v228, v246
	v_add_f32_e32 v246, v229, v246
	v_add_f32_e32 v246, v230, v246
	v_add_f32_e32 v246, v231, v246
	v_cvt_pk_bf16_f32 v68, v228, v229
	v_cvt_pk_bf16_f32 v69, v230, v231
	v_add_f32_e32 v140, v140, v246
	s_nop 0
	v_mfma_f32_16x16x32_bf16 v[18:21], v[164:167], v[66:69], v[18:21]
	v_sub_f32_e32 v232, v232, v142
	v_sub_f32_e32 v233, v233, v142
	v_exp_f32_e32 v232, v232
	v_sub_f32_e32 v234, v234, v142
	v_exp_f32_e32 v233, v233
	v_sub_f32_e32 v235, v235, v142
	v_exp_f32_e32 v234, v234
	v_exp_f32_e32 v235, v235
	s_waitcnt lgkmcnt(12)
	v_mfma_f32_16x16x32_bf16 v[22:25], v[168:171], v[66:69], v[22:25]
	v_sub_f32_e32 v236, v236, v142
	v_sub_f32_e32 v237, v237, v142
	v_exp_f32_e32 v236, v236
	v_sub_f32_e32 v238, v238, v142
	v_exp_f32_e32 v237, v237
	v_sub_f32_e32 v239, v239, v142
	v_exp_f32_e32 v238, v238
	v_exp_f32_e32 v239, v239
	s_waitcnt lgkmcnt(10)
	v_mfma_f32_16x16x32_bf16 v[10:13], v[172:175], v[66:69], v[10:13]
	v_add_f32_e32 v247, 0, v232
	v_add_f32_e32 v247, v233, v247
	v_add_f32_e32 v247, v234, v247
	v_add_f32_e32 v247, v235, v247
	v_cvt_pk_bf16_f32 v74, v232, v233
	v_cvt_pk_bf16_f32 v75, v234, v235
	v_add_f32_e32 v247, v236, v247
	v_add_f32_e32 v247, v237, v247
	s_waitcnt lgkmcnt(8)
	v_mfma_f32_16x16x32_bf16 v[2:5], v[176:179], v[66:69], v[2:5]
	v_add_f32_e32 v247, v238, v247
	v_add_f32_e32 v247, v239, v247
	v_cvt_pk_bf16_f32 v76, v236, v237
	v_cvt_pk_bf16_f32 v77, v238, v239
	v_add_f32_e32 v137, v137, v247
	s_waitcnt lgkmcnt(6)
	v_mfma_f32_16x16x32_bf16 v[30:33], v[180:183], v[74:77], v[30:33]
	s_waitcnt lgkmcnt(4)
	v_mfma_f32_16x16x32_bf16 v[26:29], v[184:187], v[74:77], v[26:29]
	s_waitcnt lgkmcnt(2)
	v_mfma_f32_16x16x32_bf16 v[14:17], v[154:157], v[74:77], v[14:17]
	s_waitcnt lgkmcnt(0)
	v_mfma_f32_16x16x32_bf16 v[6:9], v[200:203], v[74:77], v[6:9]
	s_branch .LBB0_337
